# mixer-B final group output staged in LDS and stored 16B per lane instead of 2B scattered stores
# baseline (speedup 1.0000x reference)
.LBB0_374:
	v_mbcnt_lo_u32_b32 v32, -1, 0
	v_mbcnt_hi_u32_b32 v32, -1, v32
	v_readlane_b32 s98, v253, 39
	v_readfirstlane_b32 s100, v150
	v_readfirstlane_b32 s101, v151
	s_nop 3
	v_add_u32_e32 v32, s98, v32
	v_lshlrev_b32_e32 v33, 4, v32
	v_add_u32_e32 v33, 0xc800, v33
	v_lshrrev_b32_e32 v34, 3, v32
	v_and_b32_e32 v35, 7, v32
	v_lshlrev_b32_e32 v34, 9, v34
	v_lshl_add_u32 v34, v35, 4, v34
	s_lshl_b64 s[98:99], s[4:5], 9
	s_add_u32 s98, s98, s100
	s_addc_u32 s99, s99, s101
	ds_read_b128 v[36:39], v33 offset:0
	ds_read_b128 v[40:43], v33 offset:8192
	ds_read_b128 v[44:47], v33 offset:16384
	ds_read_b128 v[48:51], v33 offset:24576
	ds_read_b128 v[52:55], v33 offset:32768
	ds_read_b128 v[56:59], v33 offset:40960
	ds_read_b128 v[60:63], v33 offset:49152
	ds_read_b128 v[64:67], v33 offset:57344
	s_waitcnt lgkmcnt(7)
	global_store_dwordx4 v34, v[36:39], s[98:99]
	s_waitcnt lgkmcnt(6)
	v_add_u32_e32 v35, 0x8000, v34
	global_store_dwordx4 v35, v[40:43], s[98:99]
	s_waitcnt lgkmcnt(5)
	v_add_u32_e32 v35, 0x10000, v34
	global_store_dwordx4 v35, v[44:47], s[98:99]
	s_waitcnt lgkmcnt(4)
	v_add_u32_e32 v35, 0x18000, v34
	global_store_dwordx4 v35, v[48:51], s[98:99]
	s_waitcnt lgkmcnt(3)
	v_add_u32_e32 v35, 0x20000, v34
	global_store_dwordx4 v35, v[52:55], s[98:99]
	s_waitcnt lgkmcnt(2)
	v_add_u32_e32 v35, 0x28000, v34
	global_store_dwordx4 v35, v[56:59], s[98:99]
	s_waitcnt lgkmcnt(1)
	v_add_u32_e32 v35, 0x30000, v34
	global_store_dwordx4 v35, v[60:63], s[98:99]
	s_waitcnt lgkmcnt(0)
	v_add_u32_e32 v35, 0x38000, v34
	global_store_dwordx4 v35, v[64:67], s[98:99]
	s_waitcnt lgkmcnt(0)
	s_barrier
	s_add_i32 s15, s15, s76
	s_cmpk_gt_i32 s15, 0xff
	s_cbranch_scc1 .LBB0_369

.LBB0_397:
	s_or_b64 exec, exec, s[10:11]
	v_add_u32_e32 v39, s24, v167
	s_waitcnt lgkmcnt(0)
	v_lshlrev_b32_e32 v32, s18, v39
	v_add_u32_e32 v36, s23, v32
	ds_read_b128 v[32:35], v174 offset:49152
	v_lshl_add_u32 v37, v36, 7, v172
	ds_read_u16 v40, v37 offset:51200
	ds_read_u16 v37, v37 offset:51264
	s_mov_b64 s[10:11], 0
	s_waitcnt lgkmcnt(2)
	v_rcp_f32_e32 v32, v32
	v_rcp_f32_e32 v33, v33
	s_waitcnt lgkmcnt(1)
	v_lshlrev_b32_e32 v40, 16, v40
	s_waitcnt lgkmcnt(0)
	v_lshlrev_b32_e32 v37, 16, v37
	v_add_f32_e32 v40, v0, v40
	v_add_f32_e32 v37, v16, v37
	v_mul_f32_e32 v40, v32, v40
	v_mul_f32_e32 v32, v32, v37
	v_lshl_add_u32 v36, v36, 7, v172
	v_cvt_pk_bf16_f32 v32, v32, s0
	ds_write_b16 v36, v32 offset:51264
	v_add_u32_e32 v32, s24, v175
	v_lshlrev_b32_e32 v32, s18, v32
	v_cvt_pk_bf16_f32 v40, v40, s0
	v_add_u32_e32 v32, s23, v32
	ds_write_b16 v36, v40 offset:51200
	v_lshl_add_u32 v36, v32, 7, v172
	ds_read_u16 v37, v36 offset:51200
	ds_read_u16 v36, v36 offset:51264
	s_waitcnt lgkmcnt(1)
	v_lshlrev_b32_e32 v37, 16, v37
	s_waitcnt lgkmcnt(0)
	v_lshlrev_b32_e32 v36, 16, v36
	v_add_f32_e32 v37, v1, v37
	v_add_f32_e32 v36, v17, v36
	v_mul_f32_e32 v37, v33, v37
	v_mul_f32_e32 v36, v33, v36
	v_lshl_add_u32 v32, v32, 7, v172
	v_cvt_pk_bf16_f32 v37, v37, s0
	v_cvt_pk_bf16_f32 v36, v36, s0
	ds_write_b16 v32, v37 offset:51200
	ds_write_b16 v32, v36 offset:51264
	v_add_u32_e32 v32, s24, v176
	v_lshlrev_b32_e32 v32, s18, v32
	v_add_u32_e32 v32, s23, v32
	v_rcp_f32_e32 v33, v34
	v_lshl_add_u32 v34, v32, 7, v172
	ds_read_u16 v36, v34 offset:51200
	ds_read_u16 v34, v34 offset:51264
	s_waitcnt lgkmcnt(1)
	v_lshlrev_b32_e32 v36, 16, v36
	s_waitcnt lgkmcnt(0)
	v_lshlrev_b32_e32 v34, 16, v34
	v_add_f32_e32 v36, v2, v36
	v_add_f32_e32 v34, v18, v34
	v_mul_f32_e32 v36, v33, v36
	v_mul_f32_e32 v34, v33, v34
	v_lshl_add_u32 v32, v32, 7, v172
	v_cvt_pk_bf16_f32 v36, v36, s0
	v_cvt_pk_bf16_f32 v34, v34, s0
	ds_write_b16 v32, v36 offset:51200
	ds_write_b16 v32, v34 offset:51264
	v_add_u32_e32 v32, s24, v177
	v_lshlrev_b32_e32 v32, s18, v32
	v_add_u32_e32 v32, s23, v32
	v_lshl_add_u32 v34, v32, 7, v172
	v_rcp_f32_e32 v33, v35
	ds_read_u16 v35, v34 offset:51200
	ds_read_u16 v34, v34 offset:51264
	s_waitcnt lgkmcnt(1)
	v_lshlrev_b32_e32 v35, 16, v35
	s_waitcnt lgkmcnt(0)
	v_lshlrev_b32_e32 v34, 16, v34
	v_add_f32_e32 v35, v3, v35
	v_add_f32_e32 v34, v19, v34
	v_mul_f32_e32 v35, v33, v35
	v_mul_f32_e32 v34, v33, v34
	v_lshl_add_u32 v32, v32, 7, v172
	v_cvt_pk_bf16_f32 v35, v35, s0
	v_cvt_pk_bf16_f32 v34, v34, s0
	ds_write_b16 v32, v35 offset:51200
	ds_write_b16 v32, v34 offset:51264
	v_add_lshl_u32 v32, v39, 8, s18
	v_add_u32_e32 v36, s23, v32
	ds_read_b128 v[32:35], v174 offset:49184
	v_lshl_add_u32 v37, v36, 7, v172
	ds_read_u16 v40, v37 offset:51200
	ds_read_u16 v37, v37 offset:51264
	s_waitcnt lgkmcnt(2)
	v_rcp_f32_e32 v32, v32
	v_rcp_f32_e32 v33, v33
	s_waitcnt lgkmcnt(1)
	v_lshlrev_b32_e32 v40, 16, v40
	s_waitcnt lgkmcnt(0)
	v_lshlrev_b32_e32 v37, 16, v37
	v_add_f32_e32 v40, v4, v40
	v_add_f32_e32 v37, v20, v37
	v_mul_f32_e32 v40, v32, v40
	v_mul_f32_e32 v32, v32, v37
	v_lshl_add_u32 v36, v36, 7, v172
	v_cvt_pk_bf16_f32 v32, v32, s0
	ds_write_b16 v36, v32 offset:51264
	v_add_lshl_u32 v32, v39, 9, s18
	v_cvt_pk_bf16_f32 v40, v40, s0
	v_add_u32_e32 v32, s23, v32
	ds_write_b16 v36, v40 offset:51200
	v_lshl_add_u32 v36, v32, 7, v172
	ds_read_u16 v37, v36 offset:51200
	ds_read_u16 v36, v36 offset:51264
	s_waitcnt lgkmcnt(1)
	v_lshlrev_b32_e32 v37, 16, v37
	s_waitcnt lgkmcnt(0)
	v_lshlrev_b32_e32 v36, 16, v36
	v_add_f32_e32 v37, v5, v37
	v_add_f32_e32 v36, v21, v36
	v_mul_f32_e32 v37, v33, v37
	v_mul_f32_e32 v36, v33, v36
	v_lshl_add_u32 v32, v32, 7, v172
	v_cvt_pk_bf16_f32 v37, v37, s0
	v_cvt_pk_bf16_f32 v36, v36, s0
	ds_write_b16 v32, v37 offset:51200
	ds_write_b16 v32, v36 offset:51264
	v_add_lshl_u32 v32, v39, 10, s18
	v_add_u32_e32 v32, s23, v32
	v_rcp_f32_e32 v33, v34
	v_lshl_add_u32 v34, v32, 7, v172
	ds_read_u16 v36, v34 offset:51200
	ds_read_u16 v34, v34 offset:51264
	s_waitcnt lgkmcnt(1)
	v_lshlrev_b32_e32 v36, 16, v36
	s_waitcnt lgkmcnt(0)
	v_lshlrev_b32_e32 v34, 16, v34
	v_add_f32_e32 v36, v6, v36
	v_add_f32_e32 v34, v22, v34
	v_mul_f32_e32 v36, v33, v36
	v_mul_f32_e32 v34, v33, v34
	v_lshl_add_u32 v32, v32, 7, v172
	v_cvt_pk_bf16_f32 v36, v36, s0
	v_cvt_pk_bf16_f32 v34, v34, s0
	ds_write_b16 v32, v36 offset:51200
	ds_write_b16 v32, v34 offset:51264
	v_add_lshl_u32 v32, v39, 11, s18
	v_add_u32_e32 v32, s23, v32
	v_lshl_add_u32 v34, v32, 7, v172
	v_rcp_f32_e32 v33, v35
	ds_read_u16 v35, v34 offset:51200
	ds_read_u16 v34, v34 offset:51264
	s_waitcnt lgkmcnt(1)
	v_lshlrev_b32_e32 v35, 16, v35
	s_waitcnt lgkmcnt(0)
	v_lshlrev_b32_e32 v34, 16, v34
	v_add_f32_e32 v35, v7, v35
	v_add_f32_e32 v34, v23, v34
	v_mul_f32_e32 v35, v33, v35
	v_mul_f32_e32 v34, v33, v34
	v_lshl_add_u32 v32, v32, 7, v172
	v_cvt_pk_bf16_f32 v35, v35, s0
	v_cvt_pk_bf16_f32 v34, v34, s0
	ds_write_b16 v32, v35 offset:51200
	ds_write_b16 v32, v34 offset:51264
	v_add_lshl_u32 v32, v39, 16, s18
	v_add_u32_e32 v36, s23, v32
	ds_read_b128 v[32:35], v174 offset:49216
	v_lshl_add_u32 v37, v36, 7, v172
	ds_read_u16 v40, v37 offset:51200
	ds_read_u16 v37, v37 offset:51264
	s_waitcnt lgkmcnt(2)
	v_rcp_f32_e32 v32, v32
	v_rcp_f32_e32 v33, v33
	s_waitcnt lgkmcnt(1)
	v_lshlrev_b32_e32 v40, 16, v40
	s_waitcnt lgkmcnt(0)
	v_lshlrev_b32_e32 v37, 16, v37
	v_add_f32_e32 v40, v8, v40
	v_add_f32_e32 v37, v24, v37
	v_mul_f32_e32 v40, v32, v40
	v_mul_f32_e32 v32, v32, v37
	v_lshl_add_u32 v36, v36, 7, v172
	v_cvt_pk_bf16_f32 v32, v32, s0
	ds_write_b16 v36, v32 offset:51264
	v_add_lshl_u32 v32, v39, 17, s18
	v_cvt_pk_bf16_f32 v40, v40, s0
	v_add_u32_e32 v32, s23, v32
	ds_write_b16 v36, v40 offset:51200
	v_lshl_add_u32 v36, v32, 7, v172
	ds_read_u16 v37, v36 offset:51200
	ds_read_u16 v36, v36 offset:51264
	s_waitcnt lgkmcnt(1)
	v_lshlrev_b32_e32 v37, 16, v37
	s_waitcnt lgkmcnt(0)
	v_lshlrev_b32_e32 v36, 16, v36
	v_add_f32_e32 v37, v9, v37
	v_add_f32_e32 v36, v25, v36
	v_mul_f32_e32 v37, v33, v37
	v_mul_f32_e32 v36, v33, v36
	v_lshl_add_u32 v32, v32, 7, v172
	v_cvt_pk_bf16_f32 v37, v37, s0
	v_cvt_pk_bf16_f32 v36, v36, s0
	ds_write_b16 v32, v37 offset:51200
	ds_write_b16 v32, v36 offset:51264
	v_add_lshl_u32 v32, v39, 18, s18
	v_add_u32_e32 v32, s23, v32
	v_rcp_f32_e32 v33, v34
	v_lshl_add_u32 v34, v32, 7, v172
	ds_read_u16 v36, v34 offset:51200
	ds_read_u16 v34, v34 offset:51264
	s_waitcnt lgkmcnt(1)
	v_lshlrev_b32_e32 v36, 16, v36
	s_waitcnt lgkmcnt(0)
	v_lshlrev_b32_e32 v34, 16, v34
	v_add_f32_e32 v36, v10, v36
	v_add_f32_e32 v34, v26, v34
	v_mul_f32_e32 v36, v33, v36
	v_mul_f32_e32 v34, v33, v34
	v_lshl_add_u32 v32, v32, 7, v172
	v_cvt_pk_bf16_f32 v36, v36, s0
	v_cvt_pk_bf16_f32 v34, v34, s0
	ds_write_b16 v32, v36 offset:51200
	ds_write_b16 v32, v34 offset:51264
	v_add_lshl_u32 v32, v39, 19, s18
	v_add_u32_e32 v32, s23, v32
	v_lshl_add_u32 v34, v32, 7, v172
	v_rcp_f32_e32 v33, v35
	ds_read_u16 v35, v34 offset:51200
	ds_read_u16 v34, v34 offset:51264
	s_waitcnt lgkmcnt(1)
	v_lshlrev_b32_e32 v35, 16, v35
	s_waitcnt lgkmcnt(0)
	v_lshlrev_b32_e32 v34, 16, v34
	v_add_f32_e32 v35, v11, v35
	v_add_f32_e32 v34, v27, v34
	v_mul_f32_e32 v35, v33, v35
	v_mul_f32_e32 v34, v33, v34
	v_lshl_add_u32 v32, v32, 7, v172
	v_cvt_pk_bf16_f32 v35, v35, s0
	v_cvt_pk_bf16_f32 v34, v34, s0
	ds_write_b16 v32, v35 offset:51200
	ds_write_b16 v32, v34 offset:51264
	v_add_lshl_u32 v32, v39, 24, s18
	v_add_u32_e32 v36, s23, v32
	ds_read_b128 v[32:35], v174 offset:49248
	v_lshl_add_u32 v37, v36, 7, v172
	ds_read_u16 v40, v37 offset:51200
	ds_read_u16 v37, v37 offset:51264
	s_waitcnt lgkmcnt(2)
	v_rcp_f32_e32 v32, v32
	v_rcp_f32_e32 v33, v33
	s_waitcnt lgkmcnt(1)
	v_lshlrev_b32_e32 v40, 16, v40
	s_waitcnt lgkmcnt(0)
	v_lshlrev_b32_e32 v37, 16, v37
	v_add_f32_e32 v40, v12, v40
	v_add_f32_e32 v37, v28, v37
	v_mul_f32_e32 v40, v32, v40
	v_mul_f32_e32 v32, v32, v37
	v_lshl_add_u32 v36, v36, 7, v172
	v_cvt_pk_bf16_f32 v32, v32, s0
	ds_write_b16 v36, v32 offset:51264
	v_add_lshl_u32 v32, v39, 25, s18
	v_cvt_pk_bf16_f32 v40, v40, s0
	v_add_u32_e32 v32, s23, v32
	ds_write_b16 v36, v40 offset:51200
	v_lshl_add_u32 v36, v32, 7, v172
	ds_read_u16 v37, v36 offset:51200
	ds_read_u16 v36, v36 offset:51264
	s_waitcnt lgkmcnt(1)
	v_lshlrev_b32_e32 v37, 16, v37
	s_waitcnt lgkmcnt(0)
	v_lshlrev_b32_e32 v36, 16, v36
	v_add_f32_e32 v37, v13, v37
	v_add_f32_e32 v36, v29, v36
	v_mul_f32_e32 v37, v33, v37
	v_mul_f32_e32 v36, v33, v36
	v_lshl_add_u32 v32, v32, 7, v172
	v_cvt_pk_bf16_f32 v37, v37, s0
	v_cvt_pk_bf16_f32 v36, v36, s0
	ds_write_b16 v32, v37 offset:51200
	ds_write_b16 v32, v36 offset:51264
	v_add_lshl_u32 v32, v39, 26, s18
	v_add_u32_e32 v32, s23, v32
	v_rcp_f32_e32 v33, v34
	v_lshl_add_u32 v34, v32, 7, v172
	ds_read_u16 v36, v34 offset:51200
	ds_read_u16 v34, v34 offset:51264
	s_waitcnt lgkmcnt(1)
	v_lshlrev_b32_e32 v36, 16, v36
	s_waitcnt lgkmcnt(0)
	v_lshlrev_b32_e32 v34, 16, v34
	v_add_f32_e32 v36, v14, v36
	v_add_f32_e32 v34, v30, v34
	v_mul_f32_e32 v36, v33, v36
	v_mul_f32_e32 v34, v33, v34
	v_lshl_add_u32 v32, v32, 7, v172
	v_cvt_pk_bf16_f32 v36, v36, s0
	v_cvt_pk_bf16_f32 v34, v34, s0
	ds_write_b16 v32, v36 offset:51200
	ds_write_b16 v32, v34 offset:51264
	v_add_lshl_u32 v32, v39, 27, s18
	v_add_u32_e32 v32, s23, v32
	v_lshl_add_u32 v34, v32, 7, v172
	v_rcp_f32_e32 v33, v35
	ds_read_u16 v35, v34 offset:51200
	ds_read_u16 v34, v34 offset:51264
	s_waitcnt lgkmcnt(1)
	v_lshlrev_b32_e32 v35, 16, v35
	s_waitcnt lgkmcnt(0)
	v_lshlrev_b32_e32 v34, 16, v34
	v_add_f32_e32 v35, v15, v35
	v_add_f32_e32 v34, v31, v34
	v_mul_f32_e32 v35, v33, v35
	v_mul_f32_e32 v34, v33, v34
	v_lshl_add_u32 v32, v32, 7, v172
	v_cvt_pk_bf16_f32 v35, v35, s0
	v_cvt_pk_bf16_f32 v34, v34, s0
	ds_write_b16 v32, v35 offset:51200
	ds_write_b16 v32, v34 offset:51264
	s_waitcnt lgkmcnt(0)

	.amdhsa_kernel _Z14fwd_megakernel4Args
		.amdhsa_group_segment_fixed_size 0
		.amdhsa_private_segment_fixed_size 0
		.amdhsa_kernarg_size 416
		.amdhsa_user_sgpr_count 2
		.amdhsa_user_sgpr_dispatch_ptr 0
		.amdhsa_user_sgpr_queue_ptr 0
		.amdhsa_user_sgpr_kernarg_segment_ptr 1
		.amdhsa_user_sgpr_dispatch_id 0
		.amdhsa_user_sgpr_kernarg_preload_length 0
		.amdhsa_user_sgpr_kernarg_preload_offset 0
		.amdhsa_user_sgpr_private_segment_size 0
		.amdhsa_uses_dynamic_stack 0
		.amdhsa_enable_private_segment 0
		.amdhsa_system_sgpr_workgroup_id_x 1
		.amdhsa_system_sgpr_workgroup_id_y 0
		.amdhsa_system_sgpr_workgroup_id_z 0
		.amdhsa_system_sgpr_workgroup_info 0
		.amdhsa_system_vgpr_workitem_id 2
		.amdhsa_next_free_vgpr 256
		.amdhsa_next_free_sgpr 102
		.amdhsa_accum_offset 256
		.amdhsa_reserve_vcc 1
		.amdhsa_float_round_mode_32 0
		.amdhsa_float_round_mode_16_64 0
		.amdhsa_float_denorm_mode_32 3
		.amdhsa_float_denorm_mode_16_64 3
		.amdhsa_dx10_clamp 1
		.amdhsa_ieee_mode 1
		.amdhsa_fp16_overflow 0
		.amdhsa_tg_split 0
		.amdhsa_exception_fp_ieee_invalid_op 0
		.amdhsa_exception_fp_denorm_src 0
		.amdhsa_exception_fp_ieee_div_zero 0
		.amdhsa_exception_fp_ieee_overflow 0
		.amdhsa_exception_fp_ieee_underflow 0
		.amdhsa_exception_fp_ieee_inexact 0
		.amdhsa_exception_int_div_zero 0
	.end_amdhsa_kernel

amdhsa.kernels:
  - .agpr_count:     0
    .args:
      - .offset:         0
        .size:           160
        .value_kind:     by_value
      - .offset:         160
        .size:           4
        .value_kind:     hidden_block_count_x
      - .offset:         164
        .size:           4
        .value_kind:     hidden_block_count_y
      - .offset:         168
        .size:           4
        .value_kind:     hidden_block_count_z
      - .offset:         172
        .size:           2
        .value_kind:     hidden_group_size_x
      - .offset:         174
        .size:           2
        .value_kind:     hidden_group_size_y
      - .offset:         176
        .size:           2
        .value_kind:     hidden_group_size_z
      - .offset:         178
        .size:           2
        .value_kind:     hidden_remainder_x
      - .offset:         180
        .size:           2
        .value_kind:     hidden_remainder_y
      - .offset:         182
        .size:           2
        .value_kind:     hidden_remainder_z
      - .offset:         200
        .size:           8
        .value_kind:     hidden_global_offset_x
      - .offset:         208
        .size:           8
        .value_kind:     hidden_global_offset_y
      - .offset:         216
        .size:           8
        .value_kind:     hidden_global_offset_z
      - .offset:         224
        .size:           2
        .value_kind:     hidden_grid_dims
      - .offset:         248
        .size:           8
        .value_kind:     hidden_multigrid_sync_arg
      - .offset:         280
        .size:           4
        .value_kind:     hidden_dynamic_lds_size
    .group_segment_fixed_size: 0
    .kernarg_segment_align: 8
    .kernarg_segment_size: 416
    .language:       OpenCL C
    .language_version:
      - 2
      - 0
    .max_flat_workgroup_size: 512
    .name:           _Z14fwd_megakernel4Args
    .private_segment_fixed_size: 0
    .sgpr_count:     108
    .sgpr_spill_count: 155
    .symbol:         _Z14fwd_megakernel4Args.kd
    .uniform_work_group_size: 1
    .uses_dynamic_stack: false
    .vgpr_count:     256
    .vgpr_spill_count: 0
    .wavefront_size: 64
